# static priority raise (s_setprio 1) for the younger wave of each SIMD (waves 4-7) through the gemm_in and gemm_out tile loops
# speedup vs baseline: 1.0044x; 1.0044x over previous
.LBB0_235:
	s_and_b32 s1, 0xffff, s1
	s_lshr_b32 s1, 0x88, s1
	s_mul_i32 s6, s1, 11
	s_cmp_ge_i32 s4, s6
	s_cbranch_scc1 .LBB0_249
	v_readfirstlane_b32 s14, v143
	s_cmp_ge_u32 s14, 0x100
	s_cbranch_scc0 .Lpr0
	s_setprio 1
.Lpr0:
	v_ashrrev_i32_e32 v1, 6, v0
	v_lshrrev_b32_e32 v3, 30, v1
	v_add_u32_e32 v3, v1, v3
	s_mul_i32 s7, s0, s1
	s_mul_i32 s0, s74, 0x580000
	v_ashrrev_i32_e32 v3, 2, v3
	s_add_u32 s0, s50, s0
	s_waitcnt vmcnt(6)
	v_and_b32_e32 v4, 7, v0
	v_mul_i32_i24_e32 v8, 4, v3
	s_addc_u32 s1, s51, 0
	v_and_b32_e32 v2, 31, v0
	v_lshlrev_b32_e32 v128, 4, v4
	v_sub_u32_e32 v9, v1, v8
	v_lshlrev_b32_e32 v153, 7, v3
	v_ashrrev_i32_e32 v152, 3, v0
	v_bfe_u32 v6, v0, 5, 1
	v_readlane_b32 s8, v253, 38
	v_lshl_add_u64 v[176:177], s[0:1], 0, v[128:129]
	s_movk_i32 s0, 0x90
	v_or_b32_e32 v3, v153, v2
	v_lshl_or_b32 v9, v9, 6, v2
	v_readlane_b32 s9, v253, 39
	v_mul_lo_u32 v7, v152, s0
	v_mul_lo_u32 v3, v3, s0
	v_lshlrev_b32_e32 v10, 4, v6
	v_mul_lo_u32 v9, v9, s0
	v_readlane_b32 s0, v255, 15
	v_readlane_b32 s1, v255, 16
	v_lshl_add_u64 v[250:251], s[8:9], 0, v[128:129]
	v_add3_u32 v154, 0, v3, v10
	v_add_u32_e32 v13, s1, v7
	v_readlane_b32 s8, v255, 17
	v_add3_u32 v155, s0, v3, v10
	v_add_u32_e32 v3, s1, v9
	s_movk_i32 s1, 0x1200
	v_add_u32_e32 v14, s8, v7
	v_readlane_b32 s8, v255, 18
	v_mul_lo_u32 v1, v1, s1
	v_lshlrev_b32_e32 v5, 3, v4
	v_add_u32_e32 v12, s0, v7
	v_add_u32_e32 v15, s8, v7
	v_readlane_b32 s8, v255, 19
	v_add_u32_e32 v1, s0, v1
	v_lshlrev_b32_e32 v2, 1, v2
	v_mul_u32_u24_e32 v6, 0x240, v6
	v_bfe_u32 v157, v0, 3, 3
	s_movk_i32 s0, 0xffc0
	v_add_u32_e32 v4, 0, v128
	v_add_u32_e32 v11, 0, v9
	s_waitcnt vmcnt(3)
	v_add_u32_e32 v16, s8, v7
	v_add_u32_e32 v9, 0, v7
	v_add_u32_e32 v17, v1, v128
	v_add3_u32 v156, v1, v2, v6
	v_mul_u32_u24_e32 v1, 0x90, v157
	v_and_or_b32 v0, v0, s0, v5
	v_lshlrev_b32_e32 v2, 6, v8
	v_mov_b32_e32 v180, 0x2000
	v_or_b32_e32 v171, 8, v157
	v_or_b32_e32 v252, 16, v157
	v_or_b32_e32 v181, 24, v157
	v_sub_u32_e32 v179, v0, v2
	s_lshl_b32 s8, s4, 8
	s_lshl_b32 s9, s5, 8
	v_add_u32_e32 v162, v4, v7
	v_add_u32_e32 v163, v11, v10
	v_add_u32_e32 v164, v12, v128
	v_add_u32_e32 v165, v13, v128
	v_add_u32_e32 v166, v14, v128
	v_add_u32_e32 v167, v15, v128
	v_add_u32_e32 v168, v16, v128
	v_add_u32_e32 v169, v3, v10
	v_add_u32_e32 v128, v9, v128
	v_add_u32_e32 v170, v17, v1
	s_branch .LBB0_239

.LBB0_248:
	s_setprio 0
	v_mov_b32_e32 v233, 0x1000
	v_mov_b32_e32 v234, v180
	v_mov_b32_e32 v180, 0x88000
	v_mov_b32_e32 v235, 0xc0
	v_mov_b32_e32 v236, 0xf149f2ca

.Lgo_235:
	s_and_b32 s1, 0xffff, s1
	s_and_b64 s[6:7], s[90:91], exec
	s_movk_i32 s6, 0x80
	s_cselect_b32 s6, s6, 0x88
	s_lshr_b32 s1, s6, s1
	s_lshl_b32 s6, s1, 2
	s_cmp_ge_i32 s4, s6
	s_cbranch_scc1 .Lgo_end
	v_readfirstlane_b32 s14, v143
	s_cmp_ge_u32 s14, 0x100
	s_cbranch_scc0 .Lpr1
	s_setprio 1
.Lpr1:
	v_ashrrev_i32_e32 v1, 6, v0
	v_lshrrev_b32_e32 v3, 30, v1
	v_add_u32_e32 v3, v1, v3
	s_mul_i32 s7, s0, s1
	s_lshl_b32 s0, s74, 21
	s_add_u32 s0, s0, 0xc40000
	v_ashrrev_i32_e32 v3, 2, v3
	s_add_u32 s0, s50, s0
	s_waitcnt vmcnt(6)
	v_and_b32_e32 v4, 7, v0
	v_mul_i32_i24_e32 v8, 4, v3
	s_addc_u32 s1, s51, 0
	v_and_b32_e32 v2, 31, v0
	v_lshlrev_b32_e32 v128, 4, v4
	v_sub_u32_e32 v9, v1, v8
	v_lshlrev_b32_e32 v153, 7, v3
	v_ashrrev_i32_e32 v152, 3, v0
	v_bfe_u32 v6, v0, 5, 1
	v_readlane_b32 s8, v253, 38
	v_lshl_add_u64 v[176:177], s[0:1], 0, v[128:129]
	s_movk_i32 s0, 0x90
	v_or_b32_e32 v3, v153, v2
	v_lshl_or_b32 v9, v9, 6, v2
	v_readlane_b32 s9, v253, 39
	v_mul_lo_u32 v7, v152, s0
	v_mul_lo_u32 v3, v3, s0
	v_lshlrev_b32_e32 v10, 4, v6
	v_mul_lo_u32 v9, v9, s0
	v_readlane_b32 s0, v255, 15
	v_readlane_b32 s1, v255, 16
	v_lshl_add_u64 v[250:251], s[8:9], 0, v[128:129]
	v_add3_u32 v154, 0, v3, v10
	v_add_u32_e32 v13, s1, v7
	v_readlane_b32 s8, v255, 17
	v_add3_u32 v155, s0, v3, v10
	v_add_u32_e32 v3, s1, v9
	s_movk_i32 s1, 0x1200
	v_add_u32_e32 v14, s8, v7
	v_readlane_b32 s8, v255, 18
	v_mul_lo_u32 v1, v1, s1
	v_lshlrev_b32_e32 v5, 3, v4
	v_add_u32_e32 v12, s0, v7
	v_add_u32_e32 v15, s8, v7
	v_readlane_b32 s8, v255, 19
	v_add_u32_e32 v1, s0, v1
	v_lshlrev_b32_e32 v2, 1, v2
	v_mul_u32_u24_e32 v6, 0x240, v6
	v_bfe_u32 v157, v0, 3, 3
	s_movk_i32 s0, 0xffc0
	v_add_u32_e32 v4, 0, v128
	v_add_u32_e32 v11, 0, v9
	s_waitcnt vmcnt(3)
	v_add_u32_e32 v16, s8, v7
	v_add_u32_e32 v9, 0, v7
	v_add_u32_e32 v17, v1, v128
	v_add3_u32 v156, v1, v2, v6
	v_mul_u32_u24_e32 v1, 0x90, v157
	v_and_or_b32 v0, v0, s0, v5
	v_lshlrev_b32_e32 v2, 6, v8
	v_mov_b32_e32 v180, 0x2000
	v_or_b32_e32 v171, 8, v157
	v_or_b32_e32 v252, 16, v157
	v_or_b32_e32 v181, 24, v157
	v_sub_u32_e32 v179, v0, v2
	s_lshl_b32 s8, s4, 8
	s_lshl_b32 s9, s5, 8
	v_add_u32_e32 v162, v4, v7
	v_add_u32_e32 v163, v11, v10
	v_add_u32_e32 v164, v12, v128
	v_add_u32_e32 v165, v13, v128
	v_add_u32_e32 v166, v14, v128
	v_add_u32_e32 v167, v15, v128
	v_add_u32_e32 v168, v16, v128
	v_add_u32_e32 v169, v3, v10
	v_add_u32_e32 v128, v9, v128
	v_add_u32_e32 v170, v17, v1
	s_branch .Lgo_239
